# v36 + nt on the final-norm output stores of P13 (never re-read by the kernel)
# baseline (speedup 1.0000x reference)
.LBB0_3496:
	s_or_b64 exec, exec, s[4:5]
	v_lshl_add_u64 v[132:133], v[132:133], 2, s[24:25]
	s_waitcnt lgkmcnt(0)
	s_barrier
	global_load_dwordx4 v[200:203], v[132:133], off
	global_load_dwordx4 v[204:207], v[132:133], off offset:16
	global_load_dwordx4 v[208:211], v[132:133], off offset:512
	global_load_dwordx4 v[212:215], v[132:133], off offset:528
	v_lshl_add_u32 v1, v1, 2, 0
	v_add_u32_e32 v1, 0x1000, v1
	ds_read2_b32 v[154:155], v1 offset1:16
	s_waitcnt lgkmcnt(0)
	v_pk_mul_f32 v[134:135], v[134:135], v[154:155] op_sel_hi:[1,0]
	v_pk_mul_f32 v[128:129], v[128:129], v[154:155] op_sel_hi:[1,0]
	s_waitcnt vmcnt(0)
	s_nop 1
	v_mov_b64_e32 v[150:151], v[200:201]
	v_mov_b64_e32 v[152:153], v[202:203]
	v_pk_mul_f32 v[150:151], v[150:151], v[134:135]
	v_pk_mul_f32 v[152:153], v[152:153], v[128:129]
	global_store_dwordx4 v[130:131], v[150:153], off nt
	v_pk_mul_f32 v[128:129], v[124:125], v[154:155] op_sel_hi:[1,0]
	v_pk_mul_f32 v[124:125], v[126:127], v[154:155] op_sel_hi:[1,0]
	s_nop 1
	v_mov_b64_e32 v[150:151], v[204:205]
	v_mov_b64_e32 v[152:153], v[206:207]
	v_pk_mul_f32 v[126:127], v[128:129], v[152:153]
	v_pk_mul_f32 v[124:125], v[124:125], v[150:151]
	global_store_dwordx4 v[130:131], v[124:127], off offset:16 nt
	v_pk_mul_f32 v[128:129], v[120:121], v[154:155] op_sel_hi:[1,0]
	v_pk_mul_f32 v[120:121], v[122:123], v[154:155] op_sel_hi:[1,0]
	s_nop 1
	v_mov_b64_e32 v[124:125], v[208:209]
	v_mov_b64_e32 v[126:127], v[210:211]
	v_pk_mul_f32 v[122:123], v[128:129], v[126:127]
	v_pk_mul_f32 v[120:121], v[120:121], v[124:125]
	global_store_dwordx4 v[130:131], v[120:123], off offset:512 nt
	v_pk_mul_f32 v[124:125], v[116:117], v[154:155] op_sel_hi:[1,0]
	v_pk_mul_f32 v[116:117], v[118:119], v[154:155] op_sel_hi:[1,0]
	s_nop 1
	v_mov_b64_e32 v[120:121], v[212:213]
	v_mov_b64_e32 v[122:123], v[214:215]
	v_pk_mul_f32 v[118:119], v[124:125], v[122:123]
	v_pk_mul_f32 v[116:117], v[116:117], v[120:121]
	global_store_dwordx4 v[130:131], v[116:119], off offset:528 nt
	v_mov_b32_e32 v120, v155
	v_pk_mul_f32 v[112:113], v[112:113], v[120:121] op_sel_hi:[1,0]
	v_pk_mul_f32 v[122:123], v[136:137], v[120:121] op_sel_hi:[1,0]
	s_nop 1
	v_mov_b64_e32 v[116:117], v[200:201]
	v_mov_b64_e32 v[118:119], v[202:203]
	v_pk_mul_f32 v[118:119], v[118:119], v[112:113]
	v_pk_mul_f32 v[116:117], v[116:117], v[122:123]
	global_store_dwordx4 v[114:115], v[116:119], off nt
	v_pk_mul_f32 v[112:113], v[108:109], v[120:121] op_sel_hi:[1,0]
	v_pk_mul_f32 v[108:109], v[110:111], v[120:121] op_sel_hi:[1,0]
	s_nop 1
	v_mov_b64_e32 v[116:117], v[204:205]
	v_mov_b64_e32 v[118:119], v[206:207]
	v_pk_mul_f32 v[110:111], v[112:113], v[118:119]
	v_pk_mul_f32 v[108:109], v[108:109], v[116:117]
	global_store_dwordx4 v[114:115], v[108:111], off offset:16 nt
	v_pk_mul_f32 v[112:113], v[104:105], v[120:121] op_sel_hi:[1,0]
	v_pk_mul_f32 v[104:105], v[106:107], v[120:121] op_sel_hi:[1,0]
	s_nop 1
	v_mov_b64_e32 v[108:109], v[208:209]
	v_mov_b64_e32 v[110:111], v[210:211]
	v_pk_mul_f32 v[106:107], v[112:113], v[110:111]
	v_pk_mul_f32 v[104:105], v[104:105], v[108:109]
	global_store_dwordx4 v[114:115], v[104:107], off offset:512 nt
	v_pk_mul_f32 v[108:109], v[100:101], v[120:121] op_sel_hi:[1,0]
	v_pk_mul_f32 v[100:101], v[102:103], v[120:121] op_sel_hi:[1,0]
	s_nop 1
	v_mov_b64_e32 v[104:105], v[212:213]
	v_mov_b64_e32 v[106:107], v[214:215]
	v_pk_mul_f32 v[102:103], v[108:109], v[106:107]
	v_pk_mul_f32 v[100:101], v[100:101], v[104:105]
	global_store_dwordx4 v[114:115], v[100:103], off offset:528 nt
	ds_read2_b32 v[104:105], v1 offset0:32 offset1:48
	s_waitcnt lgkmcnt(0)
	v_pk_mul_f32 v[106:107], v[138:139], v[104:105] op_sel_hi:[1,0]
	v_pk_mul_f32 v[96:97], v[96:97], v[104:105] op_sel_hi:[1,0]
	s_nop 1
	v_mov_b64_e32 v[100:101], v[200:201]
	v_mov_b64_e32 v[102:103], v[202:203]
	v_pk_mul_f32 v[100:101], v[100:101], v[106:107]
	v_pk_mul_f32 v[102:103], v[102:103], v[96:97]
	global_store_dwordx4 v[98:99], v[100:103], off nt
	v_pk_mul_f32 v[96:97], v[92:93], v[104:105] op_sel_hi:[1,0]
	v_pk_mul_f32 v[92:93], v[94:95], v[104:105] op_sel_hi:[1,0]
	s_nop 1
	v_mov_b64_e32 v[100:101], v[204:205]
	v_mov_b64_e32 v[102:103], v[206:207]
	v_pk_mul_f32 v[94:95], v[96:97], v[102:103]
	v_pk_mul_f32 v[92:93], v[92:93], v[100:101]
	global_store_dwordx4 v[98:99], v[92:95], off offset:16 nt
	v_pk_mul_f32 v[96:97], v[88:89], v[104:105] op_sel_hi:[1,0]
	v_pk_mul_f32 v[88:89], v[90:91], v[104:105] op_sel_hi:[1,0]
	s_nop 1
	v_mov_b64_e32 v[92:93], v[208:209]
	v_mov_b64_e32 v[94:95], v[210:211]
	v_pk_mul_f32 v[90:91], v[96:97], v[94:95]
	v_pk_mul_f32 v[88:89], v[88:89], v[92:93]
	global_store_dwordx4 v[98:99], v[88:91], off offset:512 nt
	v_pk_mul_f32 v[92:93], v[84:85], v[104:105] op_sel_hi:[1,0]
	v_pk_mul_f32 v[84:85], v[86:87], v[104:105] op_sel_hi:[1,0]
	s_nop 1
	v_mov_b64_e32 v[88:89], v[212:213]
	v_mov_b64_e32 v[90:91], v[214:215]
	v_pk_mul_f32 v[86:87], v[92:93], v[90:91]
	v_pk_mul_f32 v[84:85], v[84:85], v[88:89]
	global_store_dwordx4 v[98:99], v[84:87], off offset:528 nt
	v_mov_b32_e32 v88, v105
	v_pk_mul_f32 v[90:91], v[142:143], v[88:89] op_sel_hi:[1,0]
	v_pk_mul_f32 v[80:81], v[80:81], v[88:89] op_sel_hi:[1,0]
	s_nop 1
	v_mov_b64_e32 v[84:85], v[200:201]
	v_mov_b64_e32 v[86:87], v[202:203]
	v_pk_mul_f32 v[84:85], v[84:85], v[90:91]
	v_pk_mul_f32 v[86:87], v[86:87], v[80:81]
	global_store_dwordx4 v[82:83], v[84:87], off nt
	v_pk_mul_f32 v[80:81], v[76:77], v[88:89] op_sel_hi:[1,0]
	v_pk_mul_f32 v[76:77], v[78:79], v[88:89] op_sel_hi:[1,0]
	s_nop 1
	v_mov_b64_e32 v[84:85], v[204:205]
	v_mov_b64_e32 v[86:87], v[206:207]
	v_pk_mul_f32 v[78:79], v[80:81], v[86:87]
	v_pk_mul_f32 v[76:77], v[76:77], v[84:85]
	global_store_dwordx4 v[82:83], v[76:79], off offset:16 nt
	v_pk_mul_f32 v[80:81], v[72:73], v[88:89] op_sel_hi:[1,0]
	v_pk_mul_f32 v[72:73], v[74:75], v[88:89] op_sel_hi:[1,0]
	s_nop 1
	v_mov_b64_e32 v[76:77], v[208:209]
	v_mov_b64_e32 v[78:79], v[210:211]
	v_pk_mul_f32 v[74:75], v[80:81], v[78:79]
	v_pk_mul_f32 v[72:73], v[72:73], v[76:77]
	global_store_dwordx4 v[82:83], v[72:75], off offset:512 nt
	v_pk_mul_f32 v[76:77], v[68:69], v[88:89] op_sel_hi:[1,0]
	v_pk_mul_f32 v[68:69], v[70:71], v[88:89] op_sel_hi:[1,0]
	s_nop 1
	v_mov_b64_e32 v[72:73], v[212:213]
	v_mov_b64_e32 v[74:75], v[214:215]
	v_pk_mul_f32 v[70:71], v[76:77], v[74:75]
	v_pk_mul_f32 v[68:69], v[68:69], v[72:73]
	global_store_dwordx4 v[82:83], v[68:71], off offset:528 nt
	ds_read2_b32 v[72:73], v1 offset0:128 offset1:144
	s_waitcnt lgkmcnt(0)
	v_pk_mul_f32 v[74:75], v[144:145], v[72:73] op_sel_hi:[1,0]
	v_pk_mul_f32 v[64:65], v[64:65], v[72:73] op_sel_hi:[1,0]
	s_nop 1
	v_mov_b64_e32 v[68:69], v[200:201]
	v_mov_b64_e32 v[70:71], v[202:203]
	v_pk_mul_f32 v[68:69], v[68:69], v[74:75]
	v_pk_mul_f32 v[70:71], v[70:71], v[64:65]
	global_store_dwordx4 v[66:67], v[68:71], off nt
	v_pk_mul_f32 v[64:65], v[60:61], v[72:73] op_sel_hi:[1,0]
	v_pk_mul_f32 v[60:61], v[62:63], v[72:73] op_sel_hi:[1,0]
	s_nop 1
	v_mov_b64_e32 v[68:69], v[204:205]
	v_mov_b64_e32 v[70:71], v[206:207]
	v_pk_mul_f32 v[62:63], v[64:65], v[70:71]
	v_pk_mul_f32 v[60:61], v[60:61], v[68:69]
	global_store_dwordx4 v[66:67], v[60:63], off offset:16 nt
	v_pk_mul_f32 v[64:65], v[56:57], v[72:73] op_sel_hi:[1,0]
	v_pk_mul_f32 v[56:57], v[58:59], v[72:73] op_sel_hi:[1,0]
	s_nop 1
	v_mov_b64_e32 v[60:61], v[208:209]
	v_mov_b64_e32 v[62:63], v[210:211]
	v_pk_mul_f32 v[58:59], v[64:65], v[62:63]
	v_pk_mul_f32 v[56:57], v[56:57], v[60:61]
	global_store_dwordx4 v[66:67], v[56:59], off offset:512 nt
	v_pk_mul_f32 v[60:61], v[52:53], v[72:73] op_sel_hi:[1,0]
	v_pk_mul_f32 v[52:53], v[54:55], v[72:73] op_sel_hi:[1,0]
	s_nop 1
	v_mov_b64_e32 v[56:57], v[212:213]
	v_mov_b64_e32 v[58:59], v[214:215]
	v_pk_mul_f32 v[54:55], v[60:61], v[58:59]
	v_pk_mul_f32 v[52:53], v[52:53], v[56:57]
	global_store_dwordx4 v[66:67], v[52:55], off offset:528 nt
	v_mov_b32_e32 v56, v73
	v_pk_mul_f32 v[58:59], v[146:147], v[56:57] op_sel_hi:[1,0]
	v_pk_mul_f32 v[48:49], v[48:49], v[56:57] op_sel_hi:[1,0]
	s_nop 1
	v_mov_b64_e32 v[52:53], v[200:201]
	v_mov_b64_e32 v[54:55], v[202:203]
	v_pk_mul_f32 v[52:53], v[52:53], v[58:59]
	v_pk_mul_f32 v[54:55], v[54:55], v[48:49]
	global_store_dwordx4 v[50:51], v[52:55], off nt
	v_pk_mul_f32 v[48:49], v[44:45], v[56:57] op_sel_hi:[1,0]
	v_pk_mul_f32 v[44:45], v[46:47], v[56:57] op_sel_hi:[1,0]
	s_nop 1
	v_mov_b64_e32 v[52:53], v[204:205]
	v_mov_b64_e32 v[54:55], v[206:207]
	v_pk_mul_f32 v[46:47], v[48:49], v[54:55]
	v_pk_mul_f32 v[44:45], v[44:45], v[52:53]
	global_store_dwordx4 v[50:51], v[44:47], off offset:16 nt
	v_pk_mul_f32 v[48:49], v[40:41], v[56:57] op_sel_hi:[1,0]
	v_pk_mul_f32 v[40:41], v[42:43], v[56:57] op_sel_hi:[1,0]
	s_nop 1
	v_mov_b64_e32 v[44:45], v[208:209]
	v_mov_b64_e32 v[46:47], v[210:211]
	v_pk_mul_f32 v[42:43], v[48:49], v[46:47]
	v_pk_mul_f32 v[40:41], v[40:41], v[44:45]
	global_store_dwordx4 v[50:51], v[40:43], off offset:512 nt
	v_pk_mul_f32 v[44:45], v[36:37], v[56:57] op_sel_hi:[1,0]
	v_pk_mul_f32 v[36:37], v[38:39], v[56:57] op_sel_hi:[1,0]
	s_nop 1
	v_mov_b64_e32 v[40:41], v[212:213]
	v_mov_b64_e32 v[42:43], v[214:215]
	v_pk_mul_f32 v[38:39], v[44:45], v[42:43]
	v_pk_mul_f32 v[36:37], v[36:37], v[40:41]
	global_store_dwordx4 v[50:51], v[36:39], off offset:528 nt
	ds_read2_b32 v[40:41], v1 offset0:160 offset1:176
	s_waitcnt lgkmcnt(0)
	v_pk_mul_f32 v[42:43], v[148:149], v[40:41] op_sel_hi:[1,0]
	v_pk_mul_f32 v[32:33], v[32:33], v[40:41] op_sel_hi:[1,0]
	s_nop 1
	v_mov_b64_e32 v[36:37], v[200:201]
	v_mov_b64_e32 v[38:39], v[202:203]
	v_pk_mul_f32 v[36:37], v[36:37], v[42:43]
	v_pk_mul_f32 v[38:39], v[38:39], v[32:33]
	global_store_dwordx4 v[34:35], v[36:39], off nt
	v_pk_mul_f32 v[32:33], v[28:29], v[40:41] op_sel_hi:[1,0]
	v_pk_mul_f32 v[28:29], v[30:31], v[40:41] op_sel_hi:[1,0]
	s_nop 1
	v_mov_b64_e32 v[36:37], v[204:205]
	v_mov_b64_e32 v[38:39], v[206:207]
	v_pk_mul_f32 v[30:31], v[32:33], v[38:39]
	v_pk_mul_f32 v[28:29], v[28:29], v[36:37]
	global_store_dwordx4 v[34:35], v[28:31], off offset:16 nt
	v_pk_mul_f32 v[32:33], v[24:25], v[40:41] op_sel_hi:[1,0]
	v_pk_mul_f32 v[24:25], v[26:27], v[40:41] op_sel_hi:[1,0]
	s_nop 1
	v_mov_b64_e32 v[28:29], v[208:209]
	v_mov_b64_e32 v[30:31], v[210:211]
	v_pk_mul_f32 v[26:27], v[32:33], v[30:31]
	v_pk_mul_f32 v[24:25], v[24:25], v[28:29]
	global_store_dwordx4 v[34:35], v[24:27], off offset:512 nt
	v_pk_mul_f32 v[28:29], v[20:21], v[40:41] op_sel_hi:[1,0]
	v_pk_mul_f32 v[20:21], v[22:23], v[40:41] op_sel_hi:[1,0]
	s_nop 1
	v_mov_b64_e32 v[24:25], v[212:213]
	v_mov_b64_e32 v[26:27], v[214:215]
	v_pk_mul_f32 v[22:23], v[28:29], v[26:27]
	v_pk_mul_f32 v[20:21], v[20:21], v[24:25]
	global_store_dwordx4 v[34:35], v[20:23], off offset:528 nt
	v_mov_b32_e32 v24, v41
	v_pk_mul_f32 v[14:15], v[14:15], v[24:25] op_sel_hi:[1,0]
	v_pk_mul_f32 v[16:17], v[16:17], v[24:25] op_sel_hi:[1,0]
	v_pk_mul_f32 v[12:13], v[12:13], v[24:25] op_sel_hi:[1,0]
	v_pk_mul_f32 v[10:11], v[10:11], v[24:25] op_sel_hi:[1,0]
	v_pk_mul_f32 v[8:9], v[8:9], v[24:25] op_sel_hi:[1,0]
	v_pk_mul_f32 v[6:7], v[6:7], v[24:25] op_sel_hi:[1,0]
	v_pk_mul_f32 v[4:5], v[4:5], v[24:25] op_sel_hi:[1,0]
	v_pk_mul_f32 v[2:3], v[2:3], v[24:25] op_sel_hi:[1,0]
	s_nop 1
	v_mov_b64_e32 v[20:21], v[200:201]
	v_mov_b64_e32 v[22:23], v[202:203]
	v_pk_mul_f32 v[16:17], v[22:23], v[16:17]
	v_pk_mul_f32 v[14:15], v[20:21], v[14:15]
	global_store_dwordx4 v[18:19], v[14:17], off nt
	s_nop 1
	v_mov_b64_e32 v[14:15], v[204:205]
	v_mov_b64_e32 v[16:17], v[206:207]
	v_pk_mul_f32 v[10:11], v[10:11], v[14:15]
	v_pk_mul_f32 v[12:13], v[12:13], v[16:17]
	global_store_dwordx4 v[18:19], v[10:13], off offset:16 nt
	s_nop 1
	v_mov_b64_e32 v[10:11], v[208:209]
	v_mov_b64_e32 v[12:13], v[210:211]
	v_pk_mul_f32 v[6:7], v[6:7], v[10:11]
	v_pk_mul_f32 v[8:9], v[8:9], v[12:13]
	global_store_dwordx4 v[18:19], v[6:9], off offset:512 nt
	s_nop 1
	v_mov_b64_e32 v[6:7], v[212:213]
	v_mov_b64_e32 v[8:9], v[214:215]
	v_pk_mul_f32 v[2:3], v[2:3], v[6:7]
	v_pk_mul_f32 v[4:5], v[4:5], v[8:9]
	global_store_dwordx4 v[18:19], v[2:5], off offset:528 nt
	s_barrier
